# v43 + nt (streaming) hint on the 8 activation stores of the FFN-up conv epilogue
# baseline (speedup 1.0000x reference)
;     __device__ __forceinline__ void operator()(const f32x4 (&acc)[2][2][4][2], const Unit& u, int wr, int wc, int fr_, int fq_) const {
;     ...
;             for (int m = 0; m < 4; ++m) { const float r = rstd2048(rs, rowb + ai * HALF + m) * sx[rowb + ai * HALF + m];
; #pragma unroll
;                 for (int bj = 0; bj < 2; ++bj)
; #pragma unroll
;                     for (int n = 0; n < 2; ++n) { typedef int i32x4 __attribute__((ext_vector_type(4)));
;                         z[ai][bj][m][n] = __builtin_convertvector(__builtin_bit_cast(i32x4, acc[ai][bj][m][n]), f32x4) * (swv[bj][n] * r); } }
;     ...
;                 for (int h = 0; h < 2; ++h) {
;                     typedef float f32x2 __attribute__((ext_vector_type(2)));
;     ...
;                     const f32x2 g0 = PAIR(z[ai][0][0][n]), g1 = PAIR(z[ai][0][1][n]), g2 = PAIR(z[ai][0][2][n]), g3 = PAIR(z[ai][0][3][n]);
;                     const f32x2 u0 = PAIR(z[ai][1][0][n]), u1 = PAIR(z[ai][1][1][n]), u2 = PAIR(z[ai][1][2][n]), u3 = PAIR(z[ai][1][3][n]);
;                     const f32x2 pBg2 = PAIR(pBg), nBg2 = PAIR(nBg), pBu2 = PAIR(pBu), nBu2 = PAIR(nBu);
;                     f32x2 pg, ng, pu, nu;
;                     pg.x = dpp_shr1(pBg2.x, g3.x); pg.y = dpp_shr1(pBg2.y, g3.y); ng.x = dpp_shl1(nBg2.x, g0.x); ng.y = dpp_shl1(nBg2.y, g0.y);
;                     pu.x = dpp_shr1(pBu2.x, u3.x); pu.y = dpp_shr1(pBu2.y, u3.y); nu.x = dpp_shl1(nBu2.x, u0.x); nu.y = dpp_shl1(nBu2.y, u0.y);
;                     const f32x2 A0 = PAIR(w0g), A1 = PAIR(w1g), A2 = PAIR(w2g), AB = PAIR(bg), C0 = PAIR(w0u), C1 = PAIR(w1u), C2 = PAIR(w2u), CB = PAIR(bu);
;                     f32x2 G[4], U[4];
;                     G[0] = A0 * pg + (A1 * g0 + (A2 * g1 + AB)); G[1] = A0 * g0 + (A1 * g1 + (A2 * g2 + AB)); G[2] = A0 * g1 + (A1 * g2 + (A2 * g3 + AB)); G[3] = A0 * g2 + (A1 * g3 + (A2 * ng + AB));
;                     U[0] = C0 * pu + (C1 * u0 + (C2 * u1 + CB)); U[1] = C0 * u0 + (C1 * u1 + (C2 * u2 + CB)); U[2] = C0 * u1 + (C1 * u2 + (C2 * u3 + CB)); U[3] = C0 * u2 + (C1 * u3 + (C2 * nu + CB));
; #pragma unroll
;                     for (int m = 0; m < 4; ++m) {
;                         const f32x2 t = G[m] * (-1.4426950408889634f);
;                         f32x2 e; e.x = __builtin_amdgcn_exp2f(t.x); e.y = __builtin_amdgcn_exp2f(t.y);
;                         const f32x2 d = e + 1.0f;
.LBB0_105:
	v_cvt_f32_i32_e32 v33, v33
	v_cvt_f32_i32_e32 v32, v32
	v_cvt_f32_i32_e32 v31, v31
	v_cvt_f32_i32_e32 v30, v30
	v_cvt_f32_i32_e32 v27, v27
	v_cvt_f32_i32_e32 v26, v26
	v_mov_b32_e32 v44, v238
	v_mov_b32_e32 v45, v238
	v_cvt_f32_i32_e32 v29, v29
	v_cvt_f32_i32_e32 v28, v28
	v_mov_b32_e32 v239, v238
	v_pk_mul_f32 v[56:57], v[20:21], v[44:45]
	v_pk_mul_f32 v[120:121], v[18:19], v[238:239]
	v_pk_mul_f32 v[56:57], v[56:57], v[32:33]
	v_pk_mul_f32 v[32:33], v[22:23], v[238:239]
	v_readlane_b32 s0, v255, 0
	v_pk_mul_f32 v[120:121], v[120:121], v[30:31]
	v_pk_mul_f32 v[30:31], v[24:25], v[44:45]
	v_pk_mul_f32 v[186:187], v[32:33], v[26:27]
	v_add_u32_e32 v26, s0, v94
	v_readlane_b32 s0, v255, 1
	v_pk_mul_f32 v[44:45], v[30:31], v[28:29]
	ds_read_b128 v[26:29], v26
	v_add_u32_e32 v30, s0, v94
	ds_read_b128 v[30:33], v30
	s_waitcnt vmcnt(4)
	v_pk_fma_f32 v[188:189], v[110:111], v[154:155], v[158:159]
	s_waitcnt lgkmcnt(3)
	v_mov_b32_dpp v170, v58 row_shr:1 row_mask:0xf bank_mask:0xf
	v_mov_b32_dpp v171, v59 row_shr:1 row_mask:0xf bank_mask:0xf
	v_pk_fma_f32 v[188:189], v[146:147], v[142:143], v[188:189]
	s_waitcnt lgkmcnt(1)
	v_mov_b32_dpp v26, v146 row_shl:1 row_mask:0xf bank_mask:0xf
	v_mov_b32_dpp v27, v147 row_shl:1 row_mask:0xf bank_mask:0xf
	v_pk_fma_f32 v[170:171], v[130:131], v[170:171], v[188:189]
	v_pk_fma_f32 v[188:189], v[120:121], v[154:155], v[158:159]
	s_waitcnt lgkmcnt(0)
	v_mov_b32_dpp v30, v138 row_shl:1 row_mask:0xf bank_mask:0xf
	v_mov_b32_dpp v31, v139 row_shl:1 row_mask:0xf bank_mask:0xf
	v_pk_fma_f32 v[188:189], v[110:111], v[142:143], v[188:189]
	v_pk_fma_f32 v[26:27], v[154:155], v[26:27], v[158:159]
	v_pk_fma_f32 v[146:147], v[146:147], v[130:131], v[188:189]
	v_pk_fma_f32 v[188:189], v[58:59], v[154:155], v[158:159]
	v_pk_fma_f32 v[26:27], v[58:59], v[142:143], v[26:27]
	s_waitcnt vmcnt(0)
	v_pk_fma_f32 v[30:31], v[162:163], v[30:31], v[166:167]
	s_mov_b32 s0, 0xbfb8aa3b
	v_mov_b32_dpp v102, v62 row_shr:1 row_mask:0xf bank_mask:0xf
	v_mov_b32_dpp v103, v63 row_shr:1 row_mask:0xf bank_mask:0xf
	v_pk_fma_f32 v[188:189], v[120:121], v[142:143], v[188:189]
	v_pk_fma_f32 v[26:27], v[120:121], v[130:131], v[26:27]
	v_pk_fma_f32 v[120:121], v[62:63], v[162:163], v[166:167]
	v_pk_fma_f32 v[30:31], v[62:63], v[150:151], v[30:31]
	v_pk_mul_f32 v[62:63], v[170:171], s[0:1] op_sel_hi:[1,0]
	v_pk_fma_f32 v[58:59], v[98:99], v[162:163], v[166:167]
	v_exp_f32_e32 v62, v62
	v_exp_f32_e32 v63, v63
	v_pk_fma_f32 v[58:59], v[138:139], v[150:151], v[58:59]
	v_pk_fma_f32 v[110:111], v[110:111], v[130:131], v[188:189]
	v_pk_fma_f32 v[58:59], v[134:135], v[102:103], v[58:59]
	v_pk_add_f32 v[62:63], v[62:63], 1.0 op_sel_hi:[1,0]
	v_pk_fma_f32 v[102:103], v[186:187], v[162:163], v[166:167]
	v_rcp_f32_e32 v62, v62
	v_rcp_f32_e32 v63, v63
	v_pk_fma_f32 v[102:103], v[98:99], v[150:151], v[102:103]
	v_pk_fma_f32 v[120:121], v[186:187], v[150:151], v[120:121]
	v_pk_fma_f32 v[102:103], v[138:139], v[134:135], v[102:103]
	v_pk_mul_f32 v[58:59], v[170:171], v[58:59]
	v_pk_fma_f32 v[98:99], v[98:99], v[134:135], v[120:121]
	v_pk_mul_f32 v[120:121], v[146:147], s[0:1] op_sel_hi:[1,0]
	v_pk_mul_f32 v[58:59], v[58:59], v[62:63]
	v_pk_mul_f32 v[62:63], v[146:147], v[102:103]
	v_pk_mul_f32 v[102:103], v[110:111], s[0:1] op_sel_hi:[1,0]
	v_exp_f32_e32 v120, v120
	v_exp_f32_e32 v121, v121
	v_exp_f32_e32 v102, v102
	v_exp_f32_e32 v103, v103
	v_mov_b32_dpp v28, v148 row_shl:1 row_mask:0xf bank_mask:0xf
	v_pk_add_f32 v[120:121], v[120:121], 1.0 op_sel_hi:[1,0]
	v_mov_b32_dpp v29, v149 row_shl:1 row_mask:0xf bank_mask:0xf
	v_pk_add_f32 v[102:103], v[102:103], 1.0 op_sel_hi:[1,0]
	v_rcp_f32_e32 v120, v120
	v_rcp_f32_e32 v121, v121
	v_rcp_f32_e32 v102, v102
	v_rcp_f32_e32 v103, v103
	v_pk_fma_f32 v[28:29], v[156:157], v[28:29], v[160:161]
	v_pk_fma_f32 v[30:31], v[186:187], v[134:135], v[30:31]
	v_pk_mul_f32 v[98:99], v[110:111], v[98:99]
	v_pk_fma_f32 v[110:111], v[60:61], v[156:157], v[160:161]
	v_pk_fma_f32 v[28:29], v[60:61], v[144:145], v[28:29]
	v_pk_mul_f32 v[62:63], v[62:63], v[120:121]
	v_pk_mul_f32 v[120:121], v[26:27], s[0:1] op_sel_hi:[1,0]
	v_pk_mul_f32 v[102:103], v[98:99], v[102:103]
	v_pk_mul_f32 v[26:27], v[26:27], v[30:31]
	v_mov_b32_dpp v32, v140 row_shl:1 row_mask:0xf bank_mask:0xf
	v_mov_b32_dpp v33, v141 row_shl:1 row_mask:0xf bank_mask:0xf
	v_pk_fma_f32 v[30:31], v[112:113], v[156:157], v[160:161]
	v_pk_fma_f32 v[98:99], v[56:57], v[156:157], v[160:161]
	v_pk_fma_f32 v[110:111], v[56:57], v[144:145], v[110:111]
	v_pk_fma_f32 v[28:29], v[56:57], v[132:133], v[28:29]
	v_pk_fma_f32 v[56:57], v[100:101], v[164:165], v[168:169]
	v_mov_b32_dpp v172, v60 row_shr:1 row_mask:0xf bank_mask:0xf
	v_mov_b32_dpp v173, v61 row_shr:1 row_mask:0xf bank_mask:0xf
	v_mov_b32_dpp v104, v64 row_shr:1 row_mask:0xf bank_mask:0xf
;     __device__ __forceinline__ void operator()(const f32x4 (&acc)[2][2][4][2], const Unit& u, int wr, int wc, int fr_, int fq_) const {
;     ...
;                 const f32x4 w0g = *(const f32x4*)(cw + ch), w1g = *(const f32x4*)(cw + NZ_ + ch), w2g = *(const f32x4*)(cw + 2 * NZ_ + ch), bg = *(const f32x4*)(cb + ch);
;                 const f32x4 w0u = *(const f32x4*)(cw + DFF_ + ch), w1u = *(const f32x4*)(cw + NZ_ + DFF_ + ch), w2u = *(const f32x4*)(cw + 2 * NZ_ + DFF_ + ch), bu = *(const f32x4*)(cb + DFF_ + ch);
;     ...
;                     pg.x = dpp_shr1(pBg2.x, g3.x); pg.y = dpp_shr1(pBg2.y, g3.y); ng.x = dpp_shl1(nBg2.x, g0.x); ng.y = dpp_shl1(nBg2.y, g0.y);
;                     pu.x = dpp_shr1(pBu2.x, u3.x); pu.y = dpp_shr1(pBu2.y, u3.y); nu.x = dpp_shl1(nBu2.x, u0.x); nu.y = dpp_shl1(nBu2.y, u0.y);
;                     const f32x2 A0 = PAIR(w0g), A1 = PAIR(w1g), A2 = PAIR(w2g), AB = PAIR(bg), C0 = PAIR(w0u), C1 = PAIR(w1u), C2 = PAIR(w2u), CB = PAIR(bu);
;                     f32x2 G[4], U[4];
;                     G[0] = A0 * pg + (A1 * g0 + (A2 * g1 + AB)); G[1] = A0 * g0 + (A1 * g1 + (A2 * g2 + AB)); G[2] = A0 * g1 + (A1 * g2 + (A2 * g3 + AB)); G[3] = A0 * g2 + (A1 * g3 + (A2 * ng + AB));
;                     U[0] = C0 * pu + (C1 * u0 + (C2 * u1 + CB)); U[1] = C0 * u0 + (C1 * u1 + (C2 * u2 + CB)); U[2] = C0 * u1 + (C1 * u2 + (C2 * u3 + CB)); U[3] = C0 * u2 + (C1 * u3 + (C2 * nu + CB));
; #pragma unroll
;                     for (int m = 0; m < 4; ++m) {
;                         const f32x2 t = G[m] * (-1.4426950408889634f);
;                         f32x2 e; e.x = __builtin_amdgcn_exp2f(t.x); e.y = __builtin_amdgcn_exp2f(t.y);
;                         const f32x2 d = e + 1.0f;
;                         f32x2 r; r.x = __builtin_amdgcn_rcpf(d.x); r.y = __builtin_amdgcn_rcpf(d.y);
;                         const f32x2 q = (G[m] * U[m]) * r;
;                         o[m][2 * h] = q.x; o[m][2 * h + 1] = q.y;
;                     }
;     ...
;                 }
; #pragma unroll
;                 for (int m = 0; m < 4; ++m) { ow[m][2 * n] = cvt_pk_bf16(o[m][0], o[m][1]); ow[m][2 * n + 1] = cvt_pk_bf16(o[m][2], o[m][3]); }
;             }
; #pragma unroll
;             for (int m = 0; m < 4; ++m) { u32x4 w; w.x = ow[m][0]; w.y = ow[m][1]; w.z = ow[m][2]; w.w = ow[m][3];
;                 *(u32x4*)(ACT + (size_t)(rowb + ai * HALF + m) * DFF_ + ch0) = w; }
	v_mov_b32_dpp v105, v65 row_shr:1 row_mask:0xf bank_mask:0xf
	v_pk_fma_f32 v[30:31], v[148:149], v[144:145], v[30:31]
	v_pk_fma_f32 v[56:57], v[140:141], v[152:153], v[56:57]
	v_pk_fma_f32 v[32:33], v[164:165], v[32:33], v[168:169]
	v_pk_fma_f32 v[30:31], v[132:133], v[172:173], v[30:31]
	v_pk_fma_f32 v[56:57], v[136:137], v[104:105], v[56:57]
	v_pk_fma_f32 v[104:105], v[64:65], v[164:165], v[168:169]
	v_pk_fma_f32 v[32:33], v[64:65], v[152:153], v[32:33]
	v_pk_fma_f32 v[60:61], v[44:45], v[164:165], v[168:169]
	v_pk_fma_f32 v[104:105], v[44:45], v[152:153], v[104:105]
	v_pk_fma_f32 v[32:33], v[44:45], v[136:137], v[32:33]
	v_pk_mul_f32 v[44:45], v[30:31], s[0:1] op_sel_hi:[1,0]
	v_pk_fma_f32 v[98:99], v[112:113], v[144:145], v[98:99]
	v_exp_f32_e32 v44, v44
	v_exp_f32_e32 v45, v45
	v_pk_fma_f32 v[98:99], v[148:149], v[132:133], v[98:99]
	v_pk_fma_f32 v[60:61], v[100:101], v[152:153], v[60:61]
	v_pk_fma_f32 v[110:111], v[112:113], v[132:133], v[110:111]
	v_pk_add_f32 v[44:45], v[44:45], 1.0 op_sel_hi:[1,0]
	v_pk_fma_f32 v[60:61], v[140:141], v[136:137], v[60:61]
	v_rcp_f32_e32 v44, v44
	v_rcp_f32_e32 v45, v45
	v_pk_mul_f32 v[64:65], v[98:99], s[0:1] op_sel_hi:[1,0]
	v_pk_mul_f32 v[30:31], v[30:31], v[56:57]
	v_exp_f32_e32 v120, v120
	v_exp_f32_e32 v121, v121
	v_exp_f32_e32 v64, v64
	v_exp_f32_e32 v65, v65
	v_pk_mul_f32 v[30:31], v[30:31], v[44:45]
	v_pk_mul_f32 v[44:45], v[98:99], v[60:61]
	v_pk_mul_f32 v[56:57], v[110:111], s[0:1] op_sel_hi:[1,0]
	v_pk_mul_f32 v[60:61], v[28:29], s[0:1] op_sel_hi:[1,0]
	v_exp_f32_e32 v56, v56
	v_exp_f32_e32 v57, v57
	v_exp_f32_e32 v60, v60
	v_exp_f32_e32 v61, v61
	v_pk_add_f32 v[120:121], v[120:121], 1.0 op_sel_hi:[1,0]
	v_pk_add_f32 v[64:65], v[64:65], 1.0 op_sel_hi:[1,0]
	v_rcp_f32_e32 v120, v120
	v_rcp_f32_e32 v121, v121
	v_rcp_f32_e32 v64, v64
	v_rcp_f32_e32 v65, v65
	v_pk_add_f32 v[56:57], v[56:57], 1.0 op_sel_hi:[1,0]
	v_pk_add_f32 v[60:61], v[60:61], 1.0 op_sel_hi:[1,0]
	v_rcp_f32_e32 v56, v56
	v_rcp_f32_e32 v57, v57
	v_rcp_f32_e32 v60, v60
	v_rcp_f32_e32 v61, v61
	v_pk_fma_f32 v[100:101], v[100:101], v[136:137], v[104:105]
	v_readlane_b32 s0, v252, 18
	v_pk_mul_f32 v[26:27], v[26:27], v[120:121]
	v_pk_mul_f32 v[44:45], v[44:45], v[64:65]
	v_pk_mul_f32 v[64:65], v[110:111], v[100:101]
	v_pk_mul_f32 v[28:29], v[28:29], v[32:33]
	v_readlane_b32 s1, v252, 19
	v_pk_mul_f32 v[64:65], v[64:65], v[56:57]
	v_pk_mul_f32 v[28:29], v[28:29], v[60:61]
	v_cvt_pk_bf16_f32 v120, v58, v59
	v_cvt_pk_bf16_f32 v121, v30, v31
	v_cvt_pk_bf16_f32 v98, v62, v63
	v_cvt_pk_bf16_f32 v99, v44, v45
	v_cvt_pk_bf16_f32 v56, v102, v103
	v_cvt_pk_bf16_f32 v57, v64, v65
	v_cvt_pk_bf16_f32 v44, v26, v27
	v_mov_b64_e32 v[26:27], s[0:1]
	s_movk_i32 s4, 0x2c00
	v_cvt_pk_bf16_f32 v45, v28, v29
	v_mad_i64_i32 v[28:29], s[0:1], v220, s4, v[26:27]
	v_lshlrev_b64 v[142:143], 1, v[236:237]
	v_or_b32_e32 v190, 1, v220
	v_lshl_add_u64 v[28:29], v[28:29], 0, v[142:143]
	global_store_dwordx4 v[28:29], v[118:121], off nt
	v_mad_i64_i32 v[28:29], s[0:1], v190, s4, v[26:27]
	v_or_b32_e32 v191, 2, v220
	v_or_b32_e32 v192, 3, v220
	v_lshl_add_u64 v[28:29], v[28:29], 0, v[142:143]
	global_store_dwordx4 v[28:29], v[96:99], off nt
	v_mad_i64_i32 v[28:29], s[0:1], v191, s4, v[26:27]
	v_mad_i64_i32 v[26:27], s[0:1], v192, s4, v[26:27]
	v_lshl_add_u64 v[28:29], v[28:29], 0, v[142:143]
	v_lshl_add_u64 v[26:27], v[26:27], 0, v[142:143]
	global_store_dwordx4 v[28:29], v[54:57], off nt
	global_store_dwordx4 v[26:27], v[42:45], off nt
	global_load_dwordx4 v[62:65], v[78:79], off
	global_load_dwordx4 v[96:99], v[224:225], off
	global_load_dwordx4 v[100:103], v[226:227], off
	global_load_dwordx4 v[110:113], v[222:223], off
	global_load_dwordx4 v[28:31], v[228:229], off
	global_load_dwordx4 v[42:45], v[230:231], off
	global_load_dwordx4 v[54:57], v[232:233], off
	global_load_dwordx4 v[58:61], v[234:235], off
	v_readlane_b32 s0, v255, 12
	v_add_u32_e32 v26, 0x1100, v94
	v_add_u32_e32 v104, 0x1120, v94
	v_add_u32_e32 v33, s0, v205
	v_add_u32_e32 v27, 0x100, v33
	v_add_u32_e32 v32, 0x120, v33
	v_cndmask_b32_e64 v26, v26, v27, s[46:47]
	v_cndmask_b32_e64 v32, v104, v32, s[46:47]
	ds_read_b128 v[134:137], v26
	ds_read_b128 v[118:121], v32
	v_readlane_b32 s4, v254, 44
	v_readlane_b32 s5, v254, 45
	v_mov_b32_e32 v26, 0
	s_andn2_b64 vcc, exec, s[4:5]
	v_cndmask_b32_e64 v27, 0, 1, s[4:5]
	v_cmp_ne_u32_e64 s[0:1], 1, v27
	v_mov_b32_e32 v138, 0
	v_mov_b32_e32 v139, 0
	v_mov_b32_e32 v140, 0
	v_mov_b32_e32 v141, 0
	v_mov_b32_e32 v130, 0
	v_mov_b32_e32 v131, 0
	v_mov_b32_e32 v132, 0
	v_mov_b32_e32 v133, 0
	v_mov_b32_e32 v244, v206
	v_mov_b32_e32 v246, v202
	v_mov_b32_e32 v202, v207
	v_mov_b32_e32 v245, v221
	s_cbranch_vccnz .LBB0_107
	ds_read_b128 v[138:141], v33 offset:4096
	ds_read_b128 v[130:133], v33 offset:4128

; __device__ __forceinline__ float dpp_shr1(float old, float v) { return __builtin_bit_cast(float, __builtin_amdgcn_update_dpp(__builtin_bit_cast(int, old), __builtin_bit_cast(int, v), 0x111, 0xf, 0xf, false)); }
; __device__ __forceinline__ float dpp_shl1(float old, float v) { return __builtin_bit_cast(float, __builtin_amdgcn_update_dpp(__builtin_bit_cast(int, old), __builtin_bit_cast(int, v), 0x101, 0xf, 0xf, false)); }
; #define PAIR(v) (h == 0 ? __builtin_shufflevector(v, v, 0, 1) : __builtin_shufflevector(v, v, 2, 3))
;     __device__ __forceinline__ void operator()(const f32x4 (&acc)[2][2][4][2], const Unit& u, int wr, int wc, int fr_, int fq_) const {
;     ...
;                     for (int n = 0; n < 2; ++n) { typedef int i32x4 __attribute__((ext_vector_type(4)));
;                         z[ai][bj][m][n] = __builtin_convertvector(__builtin_bit_cast(i32x4, acc[ai][bj][m][n]), f32x4) * (swv[bj][n] * r); } }
;     ...
;                     const f32x2 g0 = PAIR(z[ai][0][0][n]), g1 = PAIR(z[ai][0][1][n]), g2 = PAIR(z[ai][0][2][n]), g3 = PAIR(z[ai][0][3][n]);
;                     const f32x2 u0 = PAIR(z[ai][1][0][n]), u1 = PAIR(z[ai][1][1][n]), u2 = PAIR(z[ai][1][2][n]), u3 = PAIR(z[ai][1][3][n]);
;                     const f32x2 pBg2 = PAIR(pBg), nBg2 = PAIR(nBg), pBu2 = PAIR(pBu), nBu2 = PAIR(nBu);
;                     f32x2 pg, ng, pu, nu;
;                     pg.x = dpp_shr1(pBg2.x, g3.x); pg.y = dpp_shr1(pBg2.y, g3.y); ng.x = dpp_shl1(nBg2.x, g0.x); ng.y = dpp_shl1(nBg2.y, g0.y);
;                     pu.x = dpp_shr1(pBu2.x, u3.x); pu.y = dpp_shr1(pBu2.y, u3.y); nu.x = dpp_shl1(nBu2.x, u0.x); nu.y = dpp_shl1(nBu2.y, u0.y);
;                     const f32x2 A0 = PAIR(w0g), A1 = PAIR(w1g), A2 = PAIR(w2g), AB = PAIR(bg), C0 = PAIR(w0u), C1 = PAIR(w1u), C2 = PAIR(w2u), CB = PAIR(bu);
;                     f32x2 G[4], U[4];
;                     G[0] = A0 * pg + (A1 * g0 + (A2 * g1 + AB)); G[1] = A0 * g0 + (A1 * g1 + (A2 * g2 + AB)); G[2] = A0 * g1 + (A1 * g2 + (A2 * g3 + AB)); G[3] = A0 * g2 + (A1 * g3 + (A2 * ng + AB));
.LBB0_109:
	v_cvt_f32_i32_e32 v9, v9
	v_cvt_f32_i32_e32 v8, v8
	v_mov_b32_e32 v12, v32
	v_mov_b32_e32 v13, v32
	v_cvt_f32_i32_e32 v5, v5
	v_cvt_f32_i32_e32 v4, v4
	s_waitcnt lgkmcnt(1)
	v_mov_b32_dpp v26, v46 row_shl:1 row_mask:0xf bank_mask:0xf
	v_mov_b32_dpp v27, v47 row_shl:1 row_mask:0xf bank_mask:0xf
	v_pk_mul_f32 v[16:17], v[24:25], v[12:13]
	v_cvt_f32_i32_e32 v7, v7
	v_cvt_f32_i32_e32 v6, v6
	v_pk_mul_f32 v[12:13], v[20:21], v[12:13]
	v_mov_b32_e32 v33, v32
	v_pk_mul_f32 v[8:9], v[12:13], v[8:9]
	s_waitcnt vmcnt(4)
	v_pk_fma_f32 v[12:13], v[82:83], v[26:27], v[90:91]
	v_pk_mul_f32 v[4:5], v[16:17], v[4:5]
	v_pk_fma_f32 v[12:13], v[66:67], v[78:79], v[12:13]
	v_pk_mul_f32 v[16:17], v[18:19], v[32:33]
	v_pk_fma_f32 v[12:13], v[86:87], v[62:63], v[12:13]
	s_mov_b32 s0, 0xbfb8aa3b
	v_cvt_f32_i32_e32 v3, v3
	v_cvt_f32_i32_e32 v2, v2
	v_pk_mul_f32 v[6:7], v[16:17], v[6:7]
	v_pk_mul_f32 v[16:17], v[12:13], s[0:1] op_sel_hi:[1,0]
	v_pk_fma_f32 v[20:21], v[66:67], v[82:83], v[90:91]
	v_exp_f32_e32 v16, v16
	v_exp_f32_e32 v17, v17
	v_pk_fma_f32 v[20:21], v[86:87], v[78:79], v[20:21]
	v_pk_mul_f32 v[22:23], v[22:23], v[32:33]
	v_pk_fma_f32 v[20:21], v[6:7], v[62:63], v[20:21]
	v_pk_mul_f32 v[2:3], v[22:23], v[2:3]
	v_pk_mul_f32 v[22:23], v[20:21], s[0:1] op_sel_hi:[1,0]
	s_waitcnt lgkmcnt(0)
	v_mov_b32_dpp v98, v50 row_shl:1 row_mask:0xf bank_mask:0xf
	v_mov_b32_dpp v99, v51 row_shl:1 row_mask:0xf bank_mask:0xf
	v_pk_add_f32 v[16:17], v[16:17], 1.0 op_sel_hi:[1,0]
	v_exp_f32_e32 v22, v22
	v_exp_f32_e32 v23, v23
	s_waitcnt vmcnt(0)
;     __device__ __forceinline__ void operator()(const f32x4 (&acc)[2][2][4][2], const Unit& u, int wr, int wc, int fr_, int fq_) const {
;     ...
;                     const f32x2 g0 = PAIR(z[ai][0][0][n]), g1 = PAIR(z[ai][0][1][n]), g2 = PAIR(z[ai][0][2][n]), g3 = PAIR(z[ai][0][3][n]);
;                     const f32x2 u0 = PAIR(z[ai][1][0][n]), u1 = PAIR(z[ai][1][1][n]), u2 = PAIR(z[ai][1][2][n]), u3 = PAIR(z[ai][1][3][n]);
;                     const f32x2 pBg2 = PAIR(pBg), nBg2 = PAIR(nBg), pBu2 = PAIR(pBu), nBu2 = PAIR(nBu);
;                     f32x2 pg, ng, pu, nu;
;                     pg.x = dpp_shr1(pBg2.x, g3.x); pg.y = dpp_shr1(pBg2.y, g3.y); ng.x = dpp_shl1(nBg2.x, g0.x); ng.y = dpp_shl1(nBg2.y, g0.y);
;                     pu.x = dpp_shr1(pBu2.x, u3.x); pu.y = dpp_shr1(pBu2.y, u3.y); nu.x = dpp_shl1(nBu2.x, u0.x); nu.y = dpp_shl1(nBu2.y, u0.y);
;                     const f32x2 A0 = PAIR(w0g), A1 = PAIR(w1g), A2 = PAIR(w2g), AB = PAIR(bg), C0 = PAIR(w0u), C1 = PAIR(w1u), C2 = PAIR(w2u), CB = PAIR(bu);
;                     f32x2 G[4], U[4];
;                     G[0] = A0 * pg + (A1 * g0 + (A2 * g1 + AB)); G[1] = A0 * g0 + (A1 * g1 + (A2 * g2 + AB)); G[2] = A0 * g1 + (A1 * g2 + (A2 * g3 + AB)); G[3] = A0 * g2 + (A1 * g3 + (A2 * ng + AB));
;                     U[0] = C0 * pu + (C1 * u0 + (C2 * u1 + CB)); U[1] = C0 * u0 + (C1 * u1 + (C2 * u2 + CB)); U[2] = C0 * u1 + (C1 * u2 + (C2 * u3 + CB)); U[3] = C0 * u2 + (C1 * u3 + (C2 * nu + CB));
; #pragma unroll
;                     for (int m = 0; m < 4; ++m) {
;                         const f32x2 t = G[m] * (-1.4426950408889634f);
;                         f32x2 e; e.x = __builtin_amdgcn_exp2f(t.x); e.y = __builtin_amdgcn_exp2f(t.y);
;                         const f32x2 d = e + 1.0f;
;                         f32x2 r; r.x = __builtin_amdgcn_rcpf(d.x); r.y = __builtin_amdgcn_rcpf(d.y);
;                         const f32x2 q = (G[m] * U[m]) * r;
;                         o[m][2 * h] = q.x; o[m][2 * h + 1] = q.y;
;                     }
;     ...
;                 }
; #pragma unroll
;                 for (int m = 0; m < 4; ++m) { ow[m][2 * n] = cvt_pk_bf16(o[m][0], o[m][1]); ow[m][2 * n + 1] = cvt_pk_bf16(o[m][2], o[m][3]); }
;             }
; #pragma unroll
;             for (int m = 0; m < 4; ++m) { u32x4 w; w.x = ow[m][0]; w.y = ow[m][1]; w.z = ow[m][2]; w.w = ow[m][3];
	v_pk_fma_f32 v[18:19], v[54:55], v[98:99], v[58:59]
	v_rcp_f32_e32 v16, v16
	v_rcp_f32_e32 v17, v17
	v_pk_fma_f32 v[18:19], v[70:71], v[40:41], v[18:19]
	v_mov_b32_dpp v102, v66 row_shr:1 row_mask:0xf bank_mask:0xf
	v_pk_fma_f32 v[18:19], v[74:75], v[36:37], v[18:19]
	v_mov_b32_dpp v103, v67 row_shr:1 row_mask:0xf bank_mask:0xf
	v_pk_mul_f32 v[12:13], v[12:13], v[18:19]
	v_pk_add_f32 v[18:19], v[22:23], 1.0 op_sel_hi:[1,0]
	v_pk_mul_f32 v[12:13], v[12:13], v[16:17]
	v_pk_fma_f32 v[16:17], v[70:71], v[54:55], v[58:59]
	v_rcp_f32_e32 v18, v18
	v_rcp_f32_e32 v19, v19
	v_pk_fma_f32 v[16:17], v[74:75], v[40:41], v[16:17]
	v_pk_fma_f32 v[22:23], v[74:75], v[54:55], v[58:59]
	v_pk_fma_f32 v[16:17], v[2:3], v[36:37], v[16:17]
	v_pk_fma_f32 v[22:23], v[2:3], v[40:41], v[22:23]
	v_pk_mul_f32 v[16:17], v[20:21], v[16:17]
	v_pk_fma_f32 v[22:23], v[50:51], v[36:37], v[22:23]
	v_pk_mul_f32 v[16:17], v[16:17], v[18:19]
	v_pk_fma_f32 v[18:19], v[86:87], v[82:83], v[90:91]
	v_pk_fma_f32 v[2:3], v[2:3], v[54:55], v[58:59]
	v_pk_fma_f32 v[18:19], v[6:7], v[78:79], v[18:19]
	v_pk_fma_f32 v[6:7], v[6:7], v[82:83], v[90:91]
	v_pk_fma_f32 v[18:19], v[46:47], v[62:63], v[18:19]
	v_pk_fma_f32 v[6:7], v[46:47], v[78:79], v[6:7]
	v_pk_mul_f32 v[20:21], v[18:19], s[0:1] op_sel_hi:[1,0]
	v_pk_fma_f32 v[6:7], v[62:63], v[102:103], v[6:7]
	v_exp_f32_e32 v20, v20
	v_exp_f32_e32 v21, v21
	v_pk_mul_f32 v[24:25], v[6:7], s[0:1] op_sel_hi:[1,0]
	v_pk_mul_f32 v[18:19], v[18:19], v[22:23]
	v_exp_f32_e32 v24, v24
	v_pk_add_f32 v[20:21], v[20:21], 1.0 op_sel_hi:[1,0]
	v_exp_f32_e32 v25, v25
	v_rcp_f32_e32 v20, v20
	v_rcp_f32_e32 v21, v21
	v_mov_b32_dpp v94, v70 row_shr:1 row_mask:0xf bank_mask:0xf
	v_mov_b32_dpp v95, v71 row_shr:1 row_mask:0xf bank_mask:0xf
	v_pk_fma_f32 v[2:3], v[50:51], v[40:41], v[2:3]
	v_pk_mul_f32 v[18:19], v[18:19], v[20:21]
	v_pk_add_f32 v[20:21], v[24:25], 1.0 op_sel_hi:[1,0]
	v_pk_fma_f32 v[2:3], v[36:37], v[94:95], v[2:3]
	v_rcp_f32_e32 v20, v20
	v_rcp_f32_e32 v21, v21
	v_pk_mul_f32 v[2:3], v[6:7], v[2:3]
	v_pk_fma_f32 v[6:7], v[8:9], v[84:85], v[92:93]
	v_pk_fma_f32 v[22:23], v[68:69], v[84:85], v[92:93]
	v_pk_mul_f32 v[2:3], v[2:3], v[20:21]
	v_pk_fma_f32 v[20:21], v[88:89], v[84:85], v[92:93]
	v_pk_fma_f32 v[24:25], v[4:5], v[56:57], v[60:61]
	v_mov_b32_dpp v104, v68 row_shr:1 row_mask:0xf bank_mask:0xf
	v_mov_b32_dpp v105, v69 row_shr:1 row_mask:0xf bank_mask:0xf
	v_mov_b32_dpp v96, v72 row_shr:1 row_mask:0xf bank_mask:0xf
	v_mov_b32_dpp v97, v73 row_shr:1 row_mask:0xf bank_mask:0xf
	v_pk_fma_f32 v[6:7], v[48:49], v[80:81], v[6:7]
	v_pk_fma_f32 v[20:21], v[8:9], v[80:81], v[20:21]
	v_pk_fma_f32 v[22:23], v[88:89], v[80:81], v[22:23]
	v_pk_fma_f32 v[24:25], v[52:53], v[42:43], v[24:25]
	v_mov_b32_dpp v28, v48 row_shl:1 row_mask:0xf bank_mask:0xf
	v_mov_b32_dpp v29, v49 row_shl:1 row_mask:0xf bank_mask:0xf
	v_pk_fma_f32 v[6:7], v[64:65], v[104:105], v[6:7]
	v_pk_fma_f32 v[20:21], v[48:49], v[64:65], v[20:21]
	v_pk_fma_f32 v[8:9], v[8:9], v[64:65], v[22:23]
	v_pk_fma_f32 v[24:25], v[38:39], v[96:97], v[24:25]
	v_pk_fma_f32 v[22:23], v[84:85], v[28:29], v[92:93]
	v_pk_fma_f32 v[26:27], v[76:77], v[56:57], v[60:61]
	v_pk_mul_f32 v[32:33], v[6:7], s[0:1] op_sel_hi:[1,0]
	v_pk_mul_f32 v[36:37], v[20:21], s[0:1] op_sel_hi:[1,0]
	v_pk_mul_f32 v[6:7], v[6:7], v[24:25]
	v_pk_mul_f32 v[24:25], v[8:9], s[0:1] op_sel_hi:[1,0]
	v_pk_fma_f32 v[22:23], v[68:69], v[80:81], v[22:23]
	v_pk_fma_f32 v[26:27], v[4:5], v[42:43], v[26:27]
	v_exp_f32_e32 v36, v36
	v_exp_f32_e32 v37, v37
	v_exp_f32_e32 v24, v24
	v_exp_f32_e32 v25, v25
	v_pk_fma_f32 v[22:23], v[88:89], v[64:65], v[22:23]
	v_pk_fma_f32 v[26:27], v[52:53], v[38:39], v[26:27]
	v_exp_f32_e32 v32, v32
	v_exp_f32_e32 v33, v33
	v_pk_mul_f32 v[20:21], v[20:21], v[26:27]
	v_pk_mul_f32 v[26:27], v[22:23], s[0:1] op_sel_hi:[1,0]
	v_pk_add_f32 v[36:37], v[36:37], 1.0 op_sel_hi:[1,0]
	v_exp_f32_e32 v26, v26
	v_exp_f32_e32 v27, v27
	v_pk_add_f32 v[24:25], v[24:25], 1.0 op_sel_hi:[1,0]
	v_pk_fma_f32 v[28:29], v[72:73], v[56:57], v[60:61]
	v_pk_add_f32 v[32:33], v[32:33], 1.0 op_sel_hi:[1,0]
	v_rcp_f32_e32 v36, v36
	v_rcp_f32_e32 v37, v37
	v_rcp_f32_e32 v24, v24
	v_rcp_f32_e32 v25, v25
	v_pk_fma_f32 v[28:29], v[76:77], v[42:43], v[28:29]
	v_rcp_f32_e32 v32, v32
	v_rcp_f32_e32 v33, v33
	v_mov_b32_dpp v100, v52 row_shl:1 row_mask:0xf bank_mask:0xf
	v_mov_b32_dpp v101, v53 row_shl:1 row_mask:0xf bank_mask:0xf
	v_pk_fma_f32 v[4:5], v[4:5], v[38:39], v[28:29]
	v_pk_add_f32 v[26:27], v[26:27], 1.0 op_sel_hi:[1,0]
	v_readlane_b32 s0, v252, 18
	v_pk_fma_f32 v[28:29], v[56:57], v[100:101], v[60:61]
	v_rcp_f32_e32 v26, v26
	v_rcp_f32_e32 v27, v27
	v_pk_mul_f32 v[4:5], v[8:9], v[4:5]
	v_readlane_b32 s1, v252, 19
	v_add_u32_e32 v44, 0x80, v220
	v_pk_fma_f32 v[28:29], v[72:73], v[42:43], v[28:29]
	v_pk_mul_f32 v[20:21], v[20:21], v[36:37]
	v_pk_mul_f32 v[4:5], v[4:5], v[24:25]
	v_cvt_pk_bf16_f32 v36, v2, v3
	v_mov_b64_e32 v[2:3], s[0:1]
	s_movk_i32 s4, 0x2c00
	v_pk_fma_f32 v[28:29], v[76:77], v[38:39], v[28:29]
	v_pk_mul_f32 v[6:7], v[6:7], v[32:33]
	v_add_u32_e32 v45, 0x81, v220
	v_cvt_pk_bf16_f32 v37, v6, v7
	v_cvt_pk_bf16_f32 v32, v18, v19
	v_cvt_pk_bf16_f32 v33, v20, v21
	v_cvt_pk_bf16_f32 v16, v16, v17
	v_cvt_pk_bf16_f32 v17, v4, v5
	v_mad_i64_i32 v[4:5], s[0:1], v44, s4, v[2:3]
	v_pk_mul_f32 v[8:9], v[22:23], v[28:29]
	v_lshl_add_u64 v[4:5], v[4:5], 0, v[142:143]
	v_pk_mul_f32 v[8:9], v[8:9], v[26:27]
	v_cvt_pk_bf16_f32 v12, v12, v13
	v_add_u32_e32 v106, 0x82, v220
	v_cvt_pk_bf16_f32 v13, v8, v9
	global_store_dwordx4 v[4:5], v[34:37], off nt
	v_mad_i64_i32 v[4:5], s[0:1], v45, s4, v[2:3]
	v_add_u32_e32 v107, 0x83, v220
	v_lshl_add_u64 v[4:5], v[4:5], 0, v[142:143]
	global_store_dwordx4 v[4:5], v[30:33], off nt
	v_mad_i64_i32 v[4:5], s[0:1], v106, s4, v[2:3]
	v_mad_i64_i32 v[2:3], s[0:1], v107, s4, v[2:3]
	v_lshl_add_u64 v[4:5], v[4:5], 0, v[142:143]
	v_lshl_add_u64 v[2:3], v[2:3], 0, v[142:143]
	global_store_dwordx4 v[4:5], v[14:17], off nt
	global_store_dwordx4 v[2:3], v[10:13], off nt
	v_readlane_b32 s0, v254, 42
	v_readlane_b32 s1, v254, 43
	s_andn2_b64 vcc, exec, s[0:1]
	s_mov_b64 s[0:1], -1
	s_cbranch_vccnz .LBB0_76
	s_and_b64 vcc, exec, s[8:9]
	s_cbranch_vccnz .LBB0_75
	s_barrier
	s_branch .LBB0_75
